# v6 plus residual-epilogue XB loads pipelined with counted waits, MLA QK software pipeline (p0+p1 per step, reads 4 steps ahead), attention O stores widened by quad transpose
# speedup vs baseline: 1.0039x; 1.0002x over previous
; DI bf16 f2bf(float f) { return (bf16)(pkbf(f, f) & 0xffffu); }
; DI int crow(int r, int hi) { return (r & 3) + 8 * (r >> 2) + 4 * hi; }
;     ...
;     if (active) {
;         if (hi == 0) li_l[r32] = l_reg;
;         asm volatile("s_waitcnt lgkmcnt(0)" ::: "memory");
;         int le = lane; asm volatile("" : "+v"(le));
;         const int r32e = le & 31, hie = le >> 5;
;         bf16* Owl = Ow + r32e;
; #pragma unroll
;         for (int r = 0; r < 16; ++r) { const int orow = crow(r, hie); const float rl = __builtin_amdgcn_rcpf(li_l[orow]); bf16* orp = Owl + (size_t)orow * ldo;
; #pragma unroll
;             for (int d0 = 0; d0 < 4; ++d0) orp[d0 * 32] = f2bf(o[d0][r] * rl); }
.LBB0_1168:
	s_or_b64 exec, exec, s[0:1]
	s_ashr_i32 s25, s24, 31
	s_lshl_b64 s[0:1], s[24:25], 13
	s_add_u32 s0, s9, s0
	s_addc_u32 s1, s10, s1
	s_lshl_b32 s24, s54, 8
	s_add_u32 s0, s0, s24
	s_addc_u32 s1, s1, 0
	v_lshrrev_b32_e32 v131, 5, v187
	v_lshl_add_u32 v130, v131, 4, s55
	v_lshlrev_b32_e32 v129, 15, v131
	v_and_b32_e32 v131, 3, v187
	v_lshl_or_b32 v129, v131, 6, v129
	v_bfe_u32 v131, v187, 2, 3
	v_lshl_or_b32 v129, v131, 3, v129
	s_waitcnt lgkmcnt(0)
	ds_read_b128 v[82:85], v130
	ds_read_b128 v[86:89], v130 offset:32
	ds_read_b128 v[90:93], v130 offset:64
	ds_read_b128 v[94:97], v130 offset:96
	v_and_b32_e32 v131, 2, v187
	v_cmp_eq_u32_e32 vcc, 0, v131
	v_and_b32_e32 v131, 1, v187
	v_mov_b32_e32 v128, 0x5040100
	v_cmp_eq_u32_e64 s[100:101], 1, v131
	v_mov_b32_e32 v131, 0x3020706
	s_nop 1
	v_cndmask_b32_e64 v128, v128, v131, s[100:101]
	s_waitcnt lgkmcnt(0)
	v_rcp_f32_e32 v82, v82
	v_rcp_f32_e32 v83, v83
	v_rcp_f32_e32 v84, v84
	v_rcp_f32_e32 v85, v85
	v_rcp_f32_e32 v86, v86
	v_rcp_f32_e32 v87, v87
	v_rcp_f32_e32 v88, v88
	v_rcp_f32_e32 v89, v89
	v_rcp_f32_e32 v90, v90
	v_rcp_f32_e32 v91, v91
	v_rcp_f32_e32 v92, v92
	v_rcp_f32_e32 v93, v93
	v_rcp_f32_e32 v94, v94
	v_rcp_f32_e32 v95, v95
	v_rcp_f32_e32 v96, v96
	v_rcp_f32_e32 v97, v97
	v_mul_f32_e32 v98, v66, v82
	v_mul_f32_e32 v99, v50, v82
	v_mul_f32_e32 v100, v34, v82
	v_mul_f32_e32 v101, v18, v82
	v_mul_f32_e32 v112, v67, v83
	v_mul_f32_e32 v113, v51, v83
	v_mul_f32_e32 v114, v35, v83
	v_mul_f32_e32 v115, v19, v83
	v_cvt_pk_bf16_f32 v102, v98, v99
	v_cvt_pk_bf16_f32 v103, v100, v101
	v_cvt_pk_bf16_f32 v116, v112, v113
	v_cvt_pk_bf16_f32 v117, v114, v115
	v_cndmask_b32_e32 v104, v102, v103, vcc
	v_cndmask_b32_e32 v118, v116, v117, vcc
	s_add_u32 s100, s0, 0x0
	s_addc_u32 s101, s1, 0
	v_mov_b32_dpp v105, v104 quad_perm:[2,3,0,1] row_mask:0xf bank_mask:0xf
	v_mov_b32_dpp v119, v118 quad_perm:[2,3,0,1] row_mask:0xf bank_mask:0xf
	v_cndmask_b32_e32 v106, v105, v102, vcc
	v_cndmask_b32_e32 v107, v103, v105, vcc
	v_cndmask_b32_e32 v120, v119, v116, vcc
	v_cndmask_b32_e32 v121, v117, v119, vcc
	v_mov_b32_dpp v108, v106 quad_perm:[1,0,3,2] row_mask:0xf bank_mask:0xf
	v_mov_b32_dpp v109, v107 quad_perm:[1,0,3,2] row_mask:0xf bank_mask:0xf
	v_mov_b32_dpp v122, v120 quad_perm:[1,0,3,2] row_mask:0xf bank_mask:0xf
	v_mov_b32_dpp v123, v121 quad_perm:[1,0,3,2] row_mask:0xf bank_mask:0xf
	v_perm_b32 v110, v108, v106, v128
	v_perm_b32 v111, v109, v107, v128
	v_perm_b32 v124, v122, v120, v128
	v_perm_b32 v125, v123, v121, v128
	global_store_dwordx2 v129, v[110:111], s[100:101]
	s_add_u32 s100, s100, 0x2000
	s_addc_u32 s101, s101, 0
	global_store_dwordx2 v129, v[124:125], s[100:101]
	v_mul_f32_e32 v98, v68, v84
	v_mul_f32_e32 v99, v52, v84
	v_mul_f32_e32 v100, v36, v84
	v_mul_f32_e32 v101, v20, v84
	v_mul_f32_e32 v112, v69, v85
	v_mul_f32_e32 v113, v53, v85
	v_mul_f32_e32 v114, v37, v85
	v_mul_f32_e32 v115, v21, v85
	v_cvt_pk_bf16_f32 v102, v98, v99
	v_cvt_pk_bf16_f32 v103, v100, v101
	v_cvt_pk_bf16_f32 v116, v112, v113
	v_cvt_pk_bf16_f32 v117, v114, v115
	v_cndmask_b32_e32 v104, v102, v103, vcc
	v_cndmask_b32_e32 v118, v116, v117, vcc
	s_add_u32 s100, s0, 0x4000
	s_addc_u32 s101, s1, 0
	v_mov_b32_dpp v105, v104 quad_perm:[2,3,0,1] row_mask:0xf bank_mask:0xf
	v_mov_b32_dpp v119, v118 quad_perm:[2,3,0,1] row_mask:0xf bank_mask:0xf
	v_cndmask_b32_e32 v106, v105, v102, vcc
	v_cndmask_b32_e32 v107, v103, v105, vcc
	v_cndmask_b32_e32 v120, v119, v116, vcc
	v_cndmask_b32_e32 v121, v117, v119, vcc
	v_mov_b32_dpp v108, v106 quad_perm:[1,0,3,2] row_mask:0xf bank_mask:0xf
	v_mov_b32_dpp v109, v107 quad_perm:[1,0,3,2] row_mask:0xf bank_mask:0xf
	v_mov_b32_dpp v122, v120 quad_perm:[1,0,3,2] row_mask:0xf bank_mask:0xf
	v_mov_b32_dpp v123, v121 quad_perm:[1,0,3,2] row_mask:0xf bank_mask:0xf
	v_perm_b32 v110, v108, v106, v128
	v_perm_b32 v111, v109, v107, v128
	v_perm_b32 v124, v122, v120, v128
	v_perm_b32 v125, v123, v121, v128
	global_store_dwordx2 v129, v[110:111], s[100:101]
	s_add_u32 s100, s100, 0x2000
	s_addc_u32 s101, s101, 0
	global_store_dwordx2 v129, v[124:125], s[100:101]
	v_mul_f32_e32 v98, v70, v86
	v_mul_f32_e32 v99, v54, v86
	v_mul_f32_e32 v100, v38, v86
	v_mul_f32_e32 v101, v22, v86
	v_mul_f32_e32 v112, v71, v87
	v_mul_f32_e32 v113, v55, v87
	v_mul_f32_e32 v114, v39, v87
	v_mul_f32_e32 v115, v23, v87
	v_cvt_pk_bf16_f32 v102, v98, v99
	v_cvt_pk_bf16_f32 v103, v100, v101
	v_cvt_pk_bf16_f32 v116, v112, v113
	v_cvt_pk_bf16_f32 v117, v114, v115
	v_cndmask_b32_e32 v104, v102, v103, vcc
	v_cndmask_b32_e32 v118, v116, v117, vcc
	s_add_u32 s100, s0, 0x10000
	s_addc_u32 s101, s1, 0
	v_mov_b32_dpp v105, v104 quad_perm:[2,3,0,1] row_mask:0xf bank_mask:0xf
	v_mov_b32_dpp v119, v118 quad_perm:[2,3,0,1] row_mask:0xf bank_mask:0xf
	v_cndmask_b32_e32 v106, v105, v102, vcc
	v_cndmask_b32_e32 v107, v103, v105, vcc
	v_cndmask_b32_e32 v120, v119, v116, vcc
	v_cndmask_b32_e32 v121, v117, v119, vcc
	v_mov_b32_dpp v108, v106 quad_perm:[1,0,3,2] row_mask:0xf bank_mask:0xf
	v_mov_b32_dpp v109, v107 quad_perm:[1,0,3,2] row_mask:0xf bank_mask:0xf
	v_mov_b32_dpp v122, v120 quad_perm:[1,0,3,2] row_mask:0xf bank_mask:0xf
	v_mov_b32_dpp v123, v121 quad_perm:[1,0,3,2] row_mask:0xf bank_mask:0xf
	v_perm_b32 v110, v108, v106, v128
	v_perm_b32 v111, v109, v107, v128
	v_perm_b32 v124, v122, v120, v128
	v_perm_b32 v125, v123, v121, v128
	global_store_dwordx2 v129, v[110:111], s[100:101]
	s_add_u32 s100, s100, 0x2000
	s_addc_u32 s101, s101, 0
	global_store_dwordx2 v129, v[124:125], s[100:101]
	v_mul_f32_e32 v98, v72, v88
	v_mul_f32_e32 v99, v56, v88
	v_mul_f32_e32 v100, v40, v88
	v_mul_f32_e32 v101, v24, v88
	v_mul_f32_e32 v112, v73, v89
; DI bf16 f2bf(float f) { return (bf16)(pkbf(f, f) & 0xffffu); }
; DI int crow(int r, int hi) { return (r & 3) + 8 * (r >> 2) + 4 * hi; }
;     ...
;         for (int r = 0; r < 16; ++r) { const int orow = crow(r, hie); const float rl = __builtin_amdgcn_rcpf(li_l[orow]); bf16* orp = Owl + (size_t)orow * ldo;
; #pragma unroll
;             for (int d0 = 0; d0 < 4; ++d0) orp[d0 * 32] = f2bf(o[d0][r] * rl); }
	v_mul_f32_e32 v113, v57, v89
	v_mul_f32_e32 v114, v41, v89
	v_mul_f32_e32 v115, v25, v89
	v_cvt_pk_bf16_f32 v102, v98, v99
	v_cvt_pk_bf16_f32 v103, v100, v101
	v_cvt_pk_bf16_f32 v116, v112, v113
	v_cvt_pk_bf16_f32 v117, v114, v115
	v_cndmask_b32_e32 v104, v102, v103, vcc
	v_cndmask_b32_e32 v118, v116, v117, vcc
	s_add_u32 s100, s0, 0x14000
	s_addc_u32 s101, s1, 0
	v_mov_b32_dpp v105, v104 quad_perm:[2,3,0,1] row_mask:0xf bank_mask:0xf
	v_mov_b32_dpp v119, v118 quad_perm:[2,3,0,1] row_mask:0xf bank_mask:0xf
	v_cndmask_b32_e32 v106, v105, v102, vcc
	v_cndmask_b32_e32 v107, v103, v105, vcc
	v_cndmask_b32_e32 v120, v119, v116, vcc
	v_cndmask_b32_e32 v121, v117, v119, vcc
	v_mov_b32_dpp v108, v106 quad_perm:[1,0,3,2] row_mask:0xf bank_mask:0xf
	v_mov_b32_dpp v109, v107 quad_perm:[1,0,3,2] row_mask:0xf bank_mask:0xf
	v_mov_b32_dpp v122, v120 quad_perm:[1,0,3,2] row_mask:0xf bank_mask:0xf
	v_mov_b32_dpp v123, v121 quad_perm:[1,0,3,2] row_mask:0xf bank_mask:0xf
	v_perm_b32 v110, v108, v106, v128
	v_perm_b32 v111, v109, v107, v128
	v_perm_b32 v124, v122, v120, v128
	v_perm_b32 v125, v123, v121, v128
	global_store_dwordx2 v129, v[110:111], s[100:101]
	s_add_u32 s100, s100, 0x2000
	s_addc_u32 s101, s101, 0
	global_store_dwordx2 v129, v[124:125], s[100:101]
	v_mul_f32_e32 v98, v74, v90
	v_mul_f32_e32 v99, v58, v90
	v_mul_f32_e32 v100, v42, v90
	v_mul_f32_e32 v101, v26, v90
	v_mul_f32_e32 v112, v75, v91
	v_mul_f32_e32 v113, v59, v91
	v_mul_f32_e32 v114, v43, v91
	v_mul_f32_e32 v115, v27, v91
	v_cvt_pk_bf16_f32 v102, v98, v99
	v_cvt_pk_bf16_f32 v103, v100, v101
	v_cvt_pk_bf16_f32 v116, v112, v113
	v_cvt_pk_bf16_f32 v117, v114, v115
	v_cndmask_b32_e32 v104, v102, v103, vcc
	v_cndmask_b32_e32 v118, v116, v117, vcc
	s_add_u32 s100, s0, 0x20000
	s_addc_u32 s101, s1, 0
	v_mov_b32_dpp v105, v104 quad_perm:[2,3,0,1] row_mask:0xf bank_mask:0xf
	v_mov_b32_dpp v119, v118 quad_perm:[2,3,0,1] row_mask:0xf bank_mask:0xf
	v_cndmask_b32_e32 v106, v105, v102, vcc
	v_cndmask_b32_e32 v107, v103, v105, vcc
	v_cndmask_b32_e32 v120, v119, v116, vcc
	v_cndmask_b32_e32 v121, v117, v119, vcc
	v_mov_b32_dpp v108, v106 quad_perm:[1,0,3,2] row_mask:0xf bank_mask:0xf
	v_mov_b32_dpp v109, v107 quad_perm:[1,0,3,2] row_mask:0xf bank_mask:0xf
	v_mov_b32_dpp v122, v120 quad_perm:[1,0,3,2] row_mask:0xf bank_mask:0xf
	v_mov_b32_dpp v123, v121 quad_perm:[1,0,3,2] row_mask:0xf bank_mask:0xf
	v_perm_b32 v110, v108, v106, v128
	v_perm_b32 v111, v109, v107, v128
	v_perm_b32 v124, v122, v120, v128
	v_perm_b32 v125, v123, v121, v128
	global_store_dwordx2 v129, v[110:111], s[100:101]
	s_add_u32 s100, s100, 0x2000
	s_addc_u32 s101, s101, 0
	global_store_dwordx2 v129, v[124:125], s[100:101]
	v_mul_f32_e32 v98, v76, v92
	v_mul_f32_e32 v99, v60, v92
	v_mul_f32_e32 v100, v44, v92
	v_mul_f32_e32 v101, v28, v92
	v_mul_f32_e32 v112, v77, v93
	v_mul_f32_e32 v113, v61, v93
	v_mul_f32_e32 v114, v45, v93
	v_mul_f32_e32 v115, v29, v93
	v_cvt_pk_bf16_f32 v102, v98, v99
	v_cvt_pk_bf16_f32 v103, v100, v101
	v_cvt_pk_bf16_f32 v116, v112, v113
	v_cvt_pk_bf16_f32 v117, v114, v115
	v_cndmask_b32_e32 v104, v102, v103, vcc
	v_cndmask_b32_e32 v118, v116, v117, vcc
	s_add_u32 s100, s0, 0x24000
	s_addc_u32 s101, s1, 0
	v_mov_b32_dpp v105, v104 quad_perm:[2,3,0,1] row_mask:0xf bank_mask:0xf
	v_mov_b32_dpp v119, v118 quad_perm:[2,3,0,1] row_mask:0xf bank_mask:0xf
	v_cndmask_b32_e32 v106, v105, v102, vcc
	v_cndmask_b32_e32 v107, v103, v105, vcc
	v_cndmask_b32_e32 v120, v119, v116, vcc
	v_cndmask_b32_e32 v121, v117, v119, vcc
	v_mov_b32_dpp v108, v106 quad_perm:[1,0,3,2] row_mask:0xf bank_mask:0xf
	v_mov_b32_dpp v109, v107 quad_perm:[1,0,3,2] row_mask:0xf bank_mask:0xf
	v_mov_b32_dpp v122, v120 quad_perm:[1,0,3,2] row_mask:0xf bank_mask:0xf
	v_mov_b32_dpp v123, v121 quad_perm:[1,0,3,2] row_mask:0xf bank_mask:0xf
	v_perm_b32 v110, v108, v106, v128
	v_perm_b32 v111, v109, v107, v128
	v_perm_b32 v124, v122, v120, v128
	v_perm_b32 v125, v123, v121, v128
	global_store_dwordx2 v129, v[110:111], s[100:101]
	s_add_u32 s100, s100, 0x2000
	s_addc_u32 s101, s101, 0
	global_store_dwordx2 v129, v[124:125], s[100:101]
	v_mul_f32_e32 v98, v78, v94
	v_mul_f32_e32 v99, v62, v94
	v_mul_f32_e32 v100, v46, v94
	v_mul_f32_e32 v101, v30, v94
	v_mul_f32_e32 v112, v79, v95
	v_mul_f32_e32 v113, v63, v95
	v_mul_f32_e32 v114, v47, v95
	v_mul_f32_e32 v115, v31, v95
	v_cvt_pk_bf16_f32 v102, v98, v99
	v_cvt_pk_bf16_f32 v103, v100, v101
	v_cvt_pk_bf16_f32 v116, v112, v113
	v_cvt_pk_bf16_f32 v117, v114, v115
	v_cndmask_b32_e32 v104, v102, v103, vcc
	v_cndmask_b32_e32 v118, v116, v117, vcc
	s_add_u32 s100, s0, 0x30000
	s_addc_u32 s101, s1, 0
	v_mov_b32_dpp v105, v104 quad_perm:[2,3,0,1] row_mask:0xf bank_mask:0xf
	v_mov_b32_dpp v119, v118 quad_perm:[2,3,0,1] row_mask:0xf bank_mask:0xf
	v_cndmask_b32_e32 v106, v105, v102, vcc
	v_cndmask_b32_e32 v107, v103, v105, vcc
	v_cndmask_b32_e32 v120, v119, v116, vcc
	v_cndmask_b32_e32 v121, v117, v119, vcc
	v_mov_b32_dpp v108, v106 quad_perm:[1,0,3,2] row_mask:0xf bank_mask:0xf
	v_mov_b32_dpp v109, v107 quad_perm:[1,0,3,2] row_mask:0xf bank_mask:0xf
	v_mov_b32_dpp v122, v120 quad_perm:[1,0,3,2] row_mask:0xf bank_mask:0xf
	v_mov_b32_dpp v123, v121 quad_perm:[1,0,3,2] row_mask:0xf bank_mask:0xf
	v_perm_b32 v110, v108, v106, v128
	v_perm_b32 v111, v109, v107, v128
	v_perm_b32 v124, v122, v120, v128
	v_perm_b32 v125, v123, v121, v128
	global_store_dwordx2 v129, v[110:111], s[100:101]
	s_add_u32 s100, s100, 0x2000
	s_addc_u32 s101, s101, 0
	global_store_dwordx2 v129, v[124:125], s[100:101]
	v_mul_f32_e32 v98, v80, v96
	v_mul_f32_e32 v99, v64, v96
	v_mul_f32_e32 v100, v48, v96
	v_mul_f32_e32 v101, v32, v96
	v_mul_f32_e32 v112, v81, v97
	v_mul_f32_e32 v113, v65, v97
	v_mul_f32_e32 v114, v49, v97
	v_mul_f32_e32 v115, v33, v97
	v_cvt_pk_bf16_f32 v102, v98, v99
	v_cvt_pk_bf16_f32 v103, v100, v101
	v_cvt_pk_bf16_f32 v116, v112, v113
	v_cvt_pk_bf16_f32 v117, v114, v115
	v_cndmask_b32_e32 v104, v102, v103, vcc
	v_cndmask_b32_e32 v118, v116, v117, vcc
	s_add_u32 s100, s0, 0x34000
	s_addc_u32 s101, s1, 0
	v_mov_b32_dpp v105, v104 quad_perm:[2,3,0,1] row_mask:0xf bank_mask:0xf
	v_mov_b32_dpp v119, v118 quad_perm:[2,3,0,1] row_mask:0xf bank_mask:0xf
	v_cndmask_b32_e32 v106, v105, v102, vcc
	v_cndmask_b32_e32 v107, v103, v105, vcc
	v_cndmask_b32_e32 v120, v119, v116, vcc
	v_cndmask_b32_e32 v121, v117, v119, vcc
	v_mov_b32_dpp v108, v106 quad_perm:[1,0,3,2] row_mask:0xf bank_mask:0xf
	v_mov_b32_dpp v109, v107 quad_perm:[1,0,3,2] row_mask:0xf bank_mask:0xf
	v_mov_b32_dpp v122, v120 quad_perm:[1,0,3,2] row_mask:0xf bank_mask:0xf
	v_mov_b32_dpp v123, v121 quad_perm:[1,0,3,2] row_mask:0xf bank_mask:0xf
	v_perm_b32 v110, v108, v106, v128
	v_perm_b32 v111, v109, v107, v128
	v_perm_b32 v124, v122, v120, v128
	v_perm_b32 v125, v123, v121, v128
	global_store_dwordx2 v129, v[110:111], s[100:101]
	s_add_u32 s100, s100, 0x2000
	s_addc_u32 s101, s101, 0
	global_store_dwordx2 v129, v[124:125], s[100:101]

; #define SBAR() __builtin_amdgcn_sched_barrier(0)
; #define KRD2(f0, f1, ka_, m_) do { KRD(f0, kbo + ka_, (m_) * 128); KRD(f1, kbo + ka_, (m_) * 128 + 8192); } while (0)
; #define KMMA(f0, f1, q_) do { p0 = __builtin_amdgcn_mfma_f32_32x32x16_bf16(f0, q_, p0, 0, 0, 0); p1 = __builtin_amdgcn_mfma_f32_32x32x16_bf16(f1, q_, p1, 0, 0, 0); } while (0)
; #define KWAIT(n_) do { asm volatile("s_waitcnt lgkmcnt(" #n_ ")" ::: "memory"); SBAR(); } while (0)
; #define PRD3(f0, f1, qf, pa_, d_) do { KRD(f0, pbo + pa_, 0); KRD(f1, pbo + pa_, 4096); KRD(qf, qpo, (d_) * 1024); } while (0)
;     ...
;             if constexpr (ABL != 3) {
;             const int kbo = (int)(uintptr_t)Ks;
;             bf16x8 fa0, fa1, fb0, fb1;
;     ...
;             KRD2(fa0, fa1, ka0, 0); KRD2(fb0, fb1, ka1, 0);
;             KWAIT(2); KMMA(fa0, fa1, qr[0]); SBAR(); KRD2(fa0, fa1, ka2, 0);
;             KWAIT(2); KMMA(fb0, fb1, qr[1]); SBAR(); KRD2(fb0, fb1, ka3, 0);
;             KWAIT(2); KMMA(fa0, fa1, qr[2]); SBAR(); KRD2(fa0, fa1, ka0, 1);
;             KWAIT(2); KMMA(fb0, fb1, qr[3]); SBAR(); KRD2(fb0, fb1, ka1, 1);
;             KWAIT(2); KMMA(fa0, fa1, qr[4]); SBAR(); KRD2(fa0, fa1, ka2, 1);
;             KWAIT(2); KMMA(fb0, fb1, qr[5]); SBAR(); KRD2(fb0, fb1, ka3, 1);
;             if constexpr (DPE == 64) {
;                 const int pbo = (int)(uintptr_t)Ps; const int qpo = (int)(uintptr_t)qpl; bf16x8 qfa, qfb;
;     ...
;                 KWAIT(2); KMMA(fa0, fa1, qr[6]); SBAR(); PRD3(fa0, fa1, qfa, pa_0, 0);
;                 KWAIT(3); KMMA(fb0, fb1, qr[7]); SBAR(); PRD3(fb0, fb1, qfb, pa_1, 1);
;                 KWAIT(3); KMMA(fa0, fa1, qfa); SBAR(); PRD3(fa0, fa1, qfa, pa_2, 2);
;                 KWAIT(3); KMMA(fb0, fb1, qfb); SBAR(); PRD3(fb0, fb1, qfb, pa_3, 3);
;                 KWAIT(3); KMMA(fa0, fa1, qfa); SBAR();
;                 KWAIT(0); KMMA(fb0, fb1, qfb);
.LBB0_1187:
	s_cmp_ge_i32 s26, s57
	s_cselect_b64 s[0:1], -1, 0
	s_xor_b64 s[50:51], s[46:47], -1
	s_or_b64 s[0:1], s[50:51], s[0:1]
	s_and_b64 vcc, exec, s[0:1]
	s_cbranch_vccnz .LBB0_1193
	s_add_i32 s0, s27, 0
	s_add_i32 s1, s0, 0x8000
	v_add_u32_e32 v196, s0, v174
	v_add_u32_e32 v197, s0, v175
	v_add_u32_e32 v198, s0, v176
	v_add_u32_e32 v199, s0, v177
	v_add_u32_e32 v162, s1, v172
	v_add_u32_e32 v163, s1, v178
	v_add_u32_e32 v164, s1, v173
	v_add_u32_e32 v165, s1, v179
	ds_read_b128 v[4:7], v196 offset:0
	ds_read_b128 v[8:11], v196 offset:8192
	ds_read_b128 v[12:15], v197 offset:0
	ds_read_b128 v[188:191], v197 offset:8192
	ds_read_b128 v[192:195], v198 offset:0
	ds_read_b128 v[214:217], v198 offset:8192
	ds_read_b128 v[218:221], v199 offset:0
	ds_read_b128 v[234:237], v199 offset:8192
	s_waitcnt lgkmcnt(6)
	v_mfma_f32_32x32x16_bf16 v[82:97], v[4:7], v[114:117], 0
	v_mfma_f32_32x32x16_bf16 v[98:113], v[8:11], v[114:117], 0
	ds_read_b128 v[238:241], v196 offset:128
	ds_read_b128 v[242:245], v196 offset:8320
	s_waitcnt lgkmcnt(6)
	v_mfma_f32_32x32x16_bf16 v[82:97], v[12:15], v[118:121], v[82:97]
	v_mfma_f32_32x32x16_bf16 v[98:113], v[188:191], v[118:121], v[98:113]
	ds_read_b128 v[246:249], v197 offset:128
	ds_read_b128 v[222:225], v197 offset:8320
	s_waitcnt lgkmcnt(6)
	v_mfma_f32_32x32x16_bf16 v[82:97], v[192:195], v[122:125], v[82:97]
	v_mfma_f32_32x32x16_bf16 v[98:113], v[214:217], v[122:125], v[98:113]
	ds_read_b128 v[4:7], v198 offset:128
	ds_read_b128 v[8:11], v198 offset:8320
	s_waitcnt lgkmcnt(6)
	v_mfma_f32_32x32x16_bf16 v[82:97], v[218:221], v[126:129], v[82:97]
	v_mfma_f32_32x32x16_bf16 v[98:113], v[234:237], v[126:129], v[98:113]
	ds_read_b128 v[12:15], v199 offset:128
	ds_read_b128 v[188:191], v199 offset:8320
	s_waitcnt lgkmcnt(6)
	v_mfma_f32_32x32x16_bf16 v[82:97], v[238:241], v[130:133], v[82:97]
	v_mfma_f32_32x32x16_bf16 v[98:113], v[242:245], v[130:133], v[98:113]
	ds_read_b128 v[192:195], v162
	ds_read_b128 v[214:217], v162 offset:4096
	ds_read_b128 v[210:213], v183 offset:0
	s_waitcnt lgkmcnt(7)
	v_mfma_f32_32x32x16_bf16 v[82:97], v[246:249], v[134:137], v[82:97]
	v_mfma_f32_32x32x16_bf16 v[98:113], v[222:225], v[134:137], v[98:113]
	ds_read_b128 v[218:221], v163
	ds_read_b128 v[234:237], v163 offset:4096
	ds_read_b128 v[202:205], v183 offset:1024
	s_waitcnt lgkmcnt(8)
	v_mfma_f32_32x32x16_bf16 v[82:97], v[4:7], v[138:141], v[82:97]
	v_mfma_f32_32x32x16_bf16 v[98:113], v[8:11], v[138:141], v[98:113]
	ds_read_b128 v[238:241], v164
	ds_read_b128 v[242:245], v164 offset:4096
	ds_read_b128 v[230:233], v183 offset:2048
	s_waitcnt lgkmcnt(9)
	v_mfma_f32_32x32x16_bf16 v[82:97], v[12:15], v[142:145], v[82:97]
	v_mfma_f32_32x32x16_bf16 v[98:113], v[188:191], v[142:145], v[98:113]
	ds_read_b128 v[246:249], v165
	ds_read_b128 v[222:225], v165 offset:4096
	ds_read_b128 v[206:209], v183 offset:3072
	s_waitcnt lgkmcnt(9)
	v_mfma_f32_32x32x16_bf16 v[82:97], v[192:195], v[210:213], v[82:97]
	v_mfma_f32_32x32x16_bf16 v[98:113], v[214:217], v[210:213], v[98:113]
	s_waitcnt lgkmcnt(6)
	v_mfma_f32_32x32x16_bf16 v[82:97], v[218:221], v[202:205], v[82:97]
	v_mfma_f32_32x32x16_bf16 v[98:113], v[234:237], v[202:205], v[98:113]
	s_waitcnt lgkmcnt(3)
	v_mfma_f32_32x32x16_bf16 v[82:97], v[238:241], v[230:233], v[82:97]
	v_mfma_f32_32x32x16_bf16 v[98:113], v[242:245], v[230:233], v[98:113]
	s_waitcnt lgkmcnt(0)
; #define SBAR() __builtin_amdgcn_sched_barrier(0)
; DI int crow(int r, int hi) { return (r & 3) + 8 * (r >> 2) + 4 * hi; }
; #define KMMA(f0, f1, q_) do { p0 = __builtin_amdgcn_mfma_f32_32x32x16_bf16(f0, q_, p0, 0, 0, 0); p1 = __builtin_amdgcn_mfma_f32_32x32x16_bf16(f1, q_, p1, 0, 0, 0); } while (0)
; #define KWAIT(n_) do { asm volatile("s_waitcnt lgkmcnt(" #n_ ")" ::: "memory"); SBAR(); } while (0)
;     ...
;                 KWAIT(0); KMMA(fb0, fb1, qfb);
;     ...
;             } else {
;                 KWAIT(2); KMMA(fa0, fa1, qr[6]); SBAR();
;                 KWAIT(0); KMMA(fb0, fb1, qr[7]);
;             }
;     ...
;             } else { asm volatile("" : "+v"(p0), "+v"(p1)); }
;             float alpha = 1.f;
;             if constexpr (ABL != 1) {
;             float pmax = p0[0];
; #pragma unroll
;             for (int r = 1; r < 16; ++r) pmax = fmaxf(pmax, p0[r]);
; #pragma unroll
;             for (int r = 0; r < 16; ++r) pmax = fmaxf(pmax, p1[r]);
;             { auto rr = __builtin_amdgcn_permlane32_swap(__float_as_uint(pmax), __float_as_uint(pmax), false, false); pmax = fmaxf(__uint_as_float(rr[0]), __uint_as_float(rr[1])); }
;             float mn;
;             if (__all(pmax - m_reg <= thr_raw)) { mn = m_reg; alpha = 1.f; }
;             else { mn = fmaxf(m_reg, pmax); alpha = __builtin_amdgcn_exp2f((m_reg - mn) * C); m_reg = mn; }
;             const float mnC = -mn * C;
; #pragma unroll
;             for (int r = 0; r < 16; ++r) { p0[r] = __builtin_amdgcn_exp2f(fmaf(p0[r], C, mnC)); p1[r] = __builtin_amdgcn_exp2f(fmaf(p1[r], C, mnC)); }
;             float ps = 0.f;
; #pragma unroll
;             for (int r = 0; r < 16; ++r) ps += p0[r] + p1[r];
;             { auto rr = __builtin_amdgcn_permlane32_swap(__float_as_uint(ps), __float_as_uint(ps), false, false); ps = __uint_as_float(rr[0]) + __uint_as_float(rr[1]); }
;             l_reg = l_reg * alpha + ps;
;             }
;             bf16x8 pa0, pa1, pa2, pa3;
;     ...
;             PK4(p0, 0, pa0); PK4(p0, 8, pa1); PK4(p1, 0, pa2); PK4(p1, 8, pa3);
;     ...
;             if (__any(alpha < 1.f)) { if (hi == 0) al_l[r32] = alpha; asm volatile("s_waitcnt lgkmcnt(0)" ::: "memory");
; #pragma unroll
;                 for (int r = 0; r < 16; ++r) { const float a = al_l[crow(r, hi)];
; #pragma unroll
;                     for (int d = 0; d < 4; ++d) o[d][r] *= a; } }
	v_mfma_f32_32x32x16_bf16 v[82:97], v[246:249], v[206:209], v[82:97]
	v_mfma_f32_32x32x16_bf16 v[98:113], v[222:225], v[206:209], v[98:113]
	s_mov_b32 s0, 0x42ddb3d8
	s_nop 10
	v_max_f32_e32 v2, v83, v83
	v_max_f32_e32 v4, v82, v82
	v_max_f32_e32 v2, v4, v2
	v_max3_f32 v2, v2, v84, v85
	v_max3_f32 v2, v2, v86, v87
	v_max3_f32 v2, v2, v88, v89
	v_max3_f32 v2, v2, v90, v91
	v_max3_f32 v2, v2, v92, v93
	v_max3_f32 v2, v2, v94, v95
	v_max3_f32 v2, v2, v96, v97
	v_max_f32_e32 v4, v185, v185
	v_max3_f32 v2, v2, v98, v99
	v_max3_f32 v2, v2, v100, v101
	v_max3_f32 v2, v2, v102, v103
	v_max3_f32 v2, v2, v104, v105
	v_max3_f32 v2, v2, v106, v107
	v_max3_f32 v2, v2, v108, v109
	v_max3_f32 v2, v2, v110, v111
	v_max3_f32 v2, v2, v112, v113
	v_mov_b32_e32 v5, v2
	s_nop 1
	v_permlane32_swap_b32_e32 v2, v5
	v_max_f32_e32 v5, v5, v5
	v_max_f32_e32 v2, v2, v2
	v_max_f32_e32 v2, v2, v5
	v_sub_f32_e32 v5, v2, v185
	v_cmp_ge_f32_e32 vcc, s0, v5
	s_cmp_eq_u64 vcc, exec
	v_max_f32_e32 v2, v4, v2
	s_cselect_b64 vcc, -1, 0
	v_sub_f32_e32 v4, v185, v2
	v_cndmask_b32_e32 v185, v2, v185, vcc
	v_mul_f32_e32 v2, 0xbdd53b94, v185
	v_fmamk_f32 v5, v82, 0x3dd53b94, v2
	v_fmamk_f32 v6, v98, 0x3dd53b94, v2
	v_fmamk_f32 v7, v83, 0x3dd53b94, v2
	v_fmamk_f32 v8, v99, 0x3dd53b94, v2
	v_fmamk_f32 v10, v100, 0x3dd53b94, v2
	v_exp_f32_e32 v5, v5
	v_exp_f32_e32 v100, v6
	v_fmamk_f32 v9, v84, 0x3dd53b94, v2
	v_fmamk_f32 v12, v101, 0x3dd53b94, v2
	v_exp_f32_e32 v6, v7
	v_exp_f32_e32 v101, v8
	v_fmamk_f32 v11, v85, 0x3dd53b94, v2
	v_fmamk_f32 v14, v102, 0x3dd53b94, v2
	v_exp_f32_e32 v7, v9
	v_exp_f32_e32 v102, v10
	v_fmamk_f32 v13, v86, 0x3dd53b94, v2
	v_fmamk_f32 v15, v87, 0x3dd53b94, v2
	v_fmamk_f32 v16, v103, 0x3dd53b94, v2
	v_fmamk_f32 v17, v88, 0x3dd53b94, v2
	v_fmamk_f32 v82, v104, 0x3dd53b94, v2
	v_fmamk_f32 v83, v89, 0x3dd53b94, v2
	v_fmamk_f32 v84, v105, 0x3dd53b94, v2
	v_fmamk_f32 v85, v90, 0x3dd53b94, v2
	v_fmamk_f32 v86, v106, 0x3dd53b94, v2
	v_fmamk_f32 v87, v91, 0x3dd53b94, v2
	v_fmamk_f32 v88, v107, 0x3dd53b94, v2
	v_fmamk_f32 v89, v92, 0x3dd53b94, v2
	v_fmamk_f32 v90, v108, 0x3dd53b94, v2
	v_fmamk_f32 v91, v93, 0x3dd53b94, v2
	v_fmamk_f32 v92, v109, 0x3dd53b94, v2
	v_fmamk_f32 v93, v94, 0x3dd53b94, v2
	v_fmamk_f32 v94, v110, 0x3dd53b94, v2
	v_fmamk_f32 v95, v95, 0x3dd53b94, v2
	v_fmamk_f32 v98, v111, 0x3dd53b94, v2
	v_fmamk_f32 v96, v96, 0x3dd53b94, v2
	v_fmamk_f32 v99, v112, 0x3dd53b94, v2
	v_fmamk_f32 v97, v97, 0x3dd53b94, v2
	v_fmac_f32_e32 v2, 0x3dd53b94, v113
	v_exp_f32_e32 v8, v11
	v_exp_f32_e32 v103, v12
	v_exp_f32_e32 v9, v13
	v_exp_f32_e32 v14, v14
	v_exp_f32_e32 v12, v83
	v_exp_f32_e32 v83, v84
	v_exp_f32_e32 v84, v86
	v_exp_f32_e32 v86, v88
	v_exp_f32_e32 v88, v90
	v_exp_f32_e32 v90, v92
	v_exp_f32_e32 v92, v94
	v_exp_f32_e32 v94, v98
	v_exp_f32_e32 v98, v2
	v_add_f32_e32 v2, v5, v100
	v_exp_f32_e32 v10, v15
	v_exp_f32_e32 v15, v16
	v_add_f32_e32 v16, v6, v101
	v_add_f32_e32 v2, 0, v2
	v_exp_f32_e32 v11, v17
	v_exp_f32_e32 v82, v82
	v_add_f32_e32 v17, v7, v102
	v_add_f32_e32 v2, v16, v2
	v_exp_f32_e32 v13, v85
	v_exp_f32_e32 v85, v87
	v_exp_f32_e32 v87, v89
	v_exp_f32_e32 v89, v91
	v_exp_f32_e32 v91, v93
	v_exp_f32_e32 v93, v95
	v_exp_f32_e32 v95, v96
	v_exp_f32_e32 v96, v99
	v_add_f32_e32 v99, v8, v103
	v_add_f32_e32 v2, v17, v2
	v_add_f32_e32 v104, v9, v14
	v_add_f32_e32 v2, v99, v2
	v_add_f32_e32 v105, v10, v15
	v_add_f32_e32 v2, v104, v2
	v_add_f32_e32 v106, v11, v82
	v_add_f32_e32 v2, v105, v2
	v_add_f32_e32 v2, v106, v2
	v_add_f32_e32 v16, v12, v83
	v_add_f32_e32 v2, v16, v2
	v_add_f32_e32 v16, v13, v84
	v_add_f32_e32 v2, v16, v2
	v_add_f32_e32 v16, v85, v86
	v_add_f32_e32 v2, v16, v2
	v_add_f32_e32 v16, v87, v88
	v_exp_f32_e32 v97, v97
	v_add_f32_e32 v2, v16, v2
	v_add_f32_e32 v16, v89, v90
	v_mul_f32_e32 v4, 0x3dd53b94, v4
	v_add_f32_e32 v2, v16, v2
	v_add_f32_e32 v16, v91, v92
	v_exp_f32_e32 v4, v4
	v_add_f32_e32 v2, v16, v2
	v_add_f32_e32 v16, v93, v94
	v_add_f32_e32 v2, v16, v2
	v_add_f32_e32 v16, v95, v96
	v_add_f32_e32 v2, v16, v2
	v_add_f32_e32 v16, v97, v98
	v_add_f32_e32 v16, v16, v2
	v_cndmask_b32_e64 v2, v4, 1.0, vcc
	v_mov_b32_e32 v17, v16
	v_cvt_pk_bf16_f32 v4, v5, v6
	v_cvt_pk_bf16_f32 v5, v7, v8
	v_cvt_pk_bf16_f32 v6, v9, v10
	v_cvt_pk_bf16_f32 v7, v11, v12
	v_cvt_pk_bf16_f32 v8, v13, v85
	v_cvt_pk_bf16_f32 v9, v87, v89
	v_cvt_pk_bf16_f32 v10, v91, v93
	v_cvt_pk_bf16_f32 v11, v95, v97
	v_cvt_pk_bf16_f32 v12, v100, v101
	v_cvt_pk_bf16_f32 v13, v102, v103
	v_cvt_pk_bf16_f32 v14, v14, v15
	v_cvt_pk_bf16_f32 v15, v82, v83
	v_cvt_pk_bf16_f32 v82, v84, v86
	v_cvt_pk_bf16_f32 v83, v88, v90
	v_cvt_pk_bf16_f32 v84, v92, v94
	v_cvt_pk_bf16_f32 v85, v96, v98
	v_permlane32_swap_b32_e32 v16, v17
	v_permlane32_swap_b32_e32 v4, v6
	v_permlane32_swap_b32_e32 v5, v7
	v_permlane32_swap_b32_e32 v8, v10
	v_permlane32_swap_b32_e32 v9, v11
	v_permlane32_swap_b32_e32 v12, v14
	v_permlane32_swap_b32_e32 v13, v15
	v_permlane32_swap_b32_e32 v82, v84
	v_permlane32_swap_b32_e32 v83, v85
	v_cmp_gt_f32_e32 vcc, 1.0, v2
	s_cbranch_vccz .LBB0_1192
	s_and_saveexec_b64 s[0:1], s[38:39]
	ds_write_b32 v184, v2 offset:128
	s_or_b64 exec, exec, s[0:1]
	s_waitcnt lgkmcnt(0)
	v_add_u32_e32 v98, s55, v171
	ds_read_b128 v[86:89], v98 offset:224
	ds_read_b128 v[90:93], v98 offset:192
	ds_read_b128 v[94:97], v98 offset:160
	ds_read_b128 v[98:101], v98 offset:128
	s_waitcnt lgkmcnt(0)
	v_pk_mul_f32 v[78:79], v[78:79], v[86:87]
	v_pk_mul_f32 v[74:75], v[74:75], v[90:91]
	v_pk_mul_f32 v[70:71], v[70:71], v[94:95]
	v_pk_mul_f32 v[80:81], v[80:81], v[88:89]
	v_pk_mul_f32 v[76:77], v[76:77], v[92:93]
	v_pk_mul_f32 v[72:73], v[72:73], v[96:97]
	v_pk_mul_f32 v[68:69], v[68:69], v[100:101]
	v_pk_mul_f32 v[66:67], v[66:67], v[98:99]
	v_pk_mul_f32 v[62:63], v[62:63], v[86:87]
	v_pk_mul_f32 v[58:59], v[58:59], v[90:91]
	v_pk_mul_f32 v[54:55], v[54:55], v[94:95]
	v_pk_mul_f32 v[64:65], v[64:65], v[88:89]
	v_pk_mul_f32 v[60:61], v[60:61], v[92:93]
	v_pk_mul_f32 v[56:57], v[56:57], v[96:97]
	v_pk_mul_f32 v[52:53], v[52:53], v[100:101]
	v_pk_mul_f32 v[50:51], v[50:51], v[98:99]
	v_pk_mul_f32 v[46:47], v[46:47], v[86:87]
	v_pk_mul_f32 v[42:43], v[42:43], v[90:91]
	v_pk_mul_f32 v[38:39], v[38:39], v[94:95]
	v_pk_mul_f32 v[48:49], v[48:49], v[88:89]
	v_pk_mul_f32 v[44:45], v[44:45], v[92:93]
	v_pk_mul_f32 v[40:41], v[40:41], v[96:97]
	v_pk_mul_f32 v[36:37], v[36:37], v[100:101]
	v_pk_mul_f32 v[34:35], v[34:35], v[98:99]
	v_pk_mul_f32 v[30:31], v[30:31], v[86:87]
	v_pk_mul_f32 v[26:27], v[26:27], v[90:91]
	v_pk_mul_f32 v[22:23], v[22:23], v[94:95]
	v_pk_mul_f32 v[32:33], v[32:33], v[88:89]
	v_pk_mul_f32 v[28:29], v[28:29], v[92:93]
	v_pk_mul_f32 v[24:25], v[24:25], v[96:97]
	v_pk_mul_f32 v[20:21], v[20:21], v[100:101]
	v_pk_mul_f32 v[18:19], v[18:19], v[98:99]

; __device__ __forceinline__ unsigned pkbf(float lo, float hi) { f32x2v v = {lo, hi}; bf16x2v b = __builtin_convertvector(v, bf16x2v); return __builtin_bit_cast(unsigned, b); }
;     __device__ __forceinline__ void operator()(const f32x4 (&acc)[2][2][4][2], const Unit& u, int wr, int wc, int fr, int fq) const {
;     ...
;                 const int r = row0 + ai * HALF + m * 16;
;                 bf16_t* xp = XB + (size_t)r * 4096 + col0; float sq = 0.f;
;                 const u32x4 o0 = *(const u32x4*)xp, o1 = *(const u32x4*)(xp + HALF);
; #pragma unroll
;                 for (int bj = 0; bj < 2; ++bj) {
;                     const u32x4 o = bj ? o1 : o0;
;                     f32x4 a = {__uint_as_float(o.x << 16), __uint_as_float(o.x & 0xffff0000u), __uint_as_float(o.y << 16), __uint_as_float(o.y & 0xffff0000u)};
;                     f32x4 b = {__uint_as_float(o.z << 16), __uint_as_float(o.z & 0xffff0000u), __uint_as_float(o.w << 16), __uint_as_float(o.w & 0xffff0000u)};
;                     a += acc[ai][bj][m][0]; b += acc[ai][bj][m][1];
;                     if (Y) { float* yp = Y + (size_t)r * 4096 + col0 + bj * HALF; *(f32x4*)yp = a; *(f32x4*)(yp + 4) = b; }
;                     else {
;                         sq += (a[0] * a[0] + a[1] * a[1]) + (a[2] * a[2] + a[3] * a[3]) + (b[0] * b[0] + b[1] * b[1]) + (b[2] * b[2] + b[3] * b[3]);
;                         u32x4 w; w.x = pkbf(a[0], a[1]); w.y = pkbf(a[2], a[3]); w.z = pkbf(b[0], b[1]); w.w = pkbf(b[2], b[3]);
;                         *(u32x4*)(xp + bj * HALF) = w; } }
;                 if (!Y) { sq += __shfl_xor(sq, 16); sq += __shfl_xor(sq, 32); if (fq == 0) unsafeAtomicAdd(ssq + r, sq); }
;             }
.LBB0_1627:
	v_lshl_add_u32 v144, s54, 8, v146
	v_ashrrev_i32_e32 v145, 31, v144
	v_lshl_or_b32 v142, s24, 8, v148
	v_lshlrev_b64 v[150:151], 13, v[144:145]
	v_ashrrev_i32_e32 v143, 31, v142
	v_lshl_add_u64 v[150:151], s[36:37], 0, v[150:151]
	v_lshl_add_u64 v[158:159], v[142:143], 1, v[150:151]
	global_load_dwordx4 v[150:153], v[158:159], off
	global_load_dwordx4 v[154:157], v[158:159], off offset:256
	s_mov_b64 s[100:101], 0x20000
	v_lshl_add_u64 v[204:205], v[158:159], 0, s[100:101]
	global_load_dwordx4 v[164:167], v[204:205], off
	global_load_dwordx4 v[168:171], v[204:205], off offset:256
	s_mov_b64 s[100:101], 0x40000
	v_lshl_add_u64 v[204:205], v[158:159], 0, s[100:101]
	global_load_dwordx4 v[172:175], v[204:205], off
	global_load_dwordx4 v[176:179], v[204:205], off offset:256
	s_mov_b64 s[100:101], 0x60000
	v_lshl_add_u64 v[204:205], v[158:159], 0, s[100:101]
	global_load_dwordx4 v[180:183], v[204:205], off
	global_load_dwordx4 v[184:187], v[204:205], off offset:256
	s_mov_b64 s[100:101], 0x100000
	v_lshl_add_u64 v[204:205], v[158:159], 0, s[100:101]
	global_load_dwordx4 v[188:191], v[204:205], off
	global_load_dwordx4 v[192:195], v[204:205], off offset:256
	s_mov_b64 s[100:101], 0x120000
	v_lshl_add_u64 v[204:205], v[158:159], 0, s[100:101]
	global_load_dwordx4 v[196:199], v[204:205], off
	global_load_dwordx4 v[200:203], v[204:205], off offset:256
	s_waitcnt vmcnt(10)
	v_lshlrev_b32_e32 v160, 16, v150
	v_and_b32_e32 v161, 0xffff0000, v150
	v_lshlrev_b32_e32 v150, 16, v151
	v_and_b32_e32 v151, 0xffff0000, v151
	v_lshlrev_b32_e32 v162, 16, v152
	v_and_b32_e32 v163, 0xffff0000, v152
	v_lshlrev_b32_e32 v152, 16, v153
	v_and_b32_e32 v153, 0xffff0000, v153
	v_pk_add_f32 v[130:131], v[130:131], v[150:151]
	v_pk_add_f32 v[128:129], v[128:129], v[160:161]
	v_pk_add_f32 v[150:151], v[126:127], v[152:153]
	v_pk_add_f32 v[126:127], v[124:125], v[162:163]
	v_mul_f32_e32 v1, v129, v129
	v_mul_f32_e32 v124, v131, v131
	v_fmac_f32_e32 v1, v128, v128
	v_fmac_f32_e32 v124, v130, v130
	v_add_f32_e32 v1, v1, v124
	v_mul_f32_e32 v124, v127, v127
	v_fmac_f32_e32 v124, v126, v126
	v_add_f32_e32 v1, v124, v1
	v_mul_f32_e32 v124, v151, v151
	v_fmac_f32_e32 v124, v150, v150
	v_add_f32_e32 v1, v124, v1
	v_cvt_pk_bf16_f32 v124, v128, v129
	v_cvt_pk_bf16_f32 v125, v130, v131
	v_cvt_pk_bf16_f32 v126, v126, v127
	v_cvt_pk_bf16_f32 v127, v150, v151
	global_store_dwordx4 v[158:159], v[124:127], off
	v_lshlrev_b32_e32 v128, 16, v156
	v_and_b32_e32 v129, 0xffff0000, v156
	v_lshlrev_b32_e32 v124, 16, v154
	v_and_b32_e32 v125, 0xffff0000, v154
	v_lshlrev_b32_e32 v126, 16, v155
	v_and_b32_e32 v127, 0xffff0000, v155
	v_lshlrev_b32_e32 v130, 16, v157
	v_and_b32_e32 v131, 0xffff0000, v157
	v_pk_add_f32 v[122:123], v[122:123], v[126:127]
	v_pk_add_f32 v[120:121], v[120:121], v[124:125]
	v_pk_add_f32 v[124:125], v[118:119], v[130:131]
	v_pk_add_f32 v[118:119], v[116:117], v[128:129]
	v_mul_f32_e32 v116, v121, v121
	v_mul_f32_e32 v117, v123, v123
	v_fmac_f32_e32 v116, v120, v120
	v_fmac_f32_e32 v117, v122, v122
	v_add_f32_e32 v116, v116, v117
	v_mul_f32_e32 v117, v119, v119
	v_fmac_f32_e32 v117, v118, v118
	v_add_f32_e32 v116, v117, v116
	v_mul_f32_e32 v117, v125, v125
	v_fmac_f32_e32 v117, v124, v124
	v_add_f32_e32 v116, v117, v116
	v_add_f32_e32 v1, v1, v116
	v_cvt_pk_bf16_f32 v116, v120, v121
	v_cvt_pk_bf16_f32 v117, v122, v123
	v_cvt_pk_bf16_f32 v118, v118, v119
	v_cvt_pk_bf16_f32 v119, v124, v125
	global_store_dwordx4 v[158:159], v[116:119], off offset:256
	s_nop 1
	v_and_b32_e32 v117, 64, v229
	v_xor_b32_e32 v116, 16, v229
	v_add_u32_e32 v117, 64, v117
	v_cmp_lt_i32_e32 vcc, v116, v117
	s_nop 1
	v_cndmask_b32_e32 v116, v229, v116, vcc
	v_lshlrev_b32_e32 v120, 2, v116
	ds_bpermute_b32 v116, v120, v1
	s_waitcnt lgkmcnt(0)
	v_add_f32_e32 v116, v1, v116
	v_xor_b32_e32 v1, 32, v229
	v_cmp_lt_i32_e32 vcc, v1, v117
	s_nop 1
	v_cndmask_b32_e32 v1, v229, v1, vcc
	v_lshlrev_b32_e32 v121, 2, v1
	ds_bpermute_b32 v117, v121, v116
	s_and_saveexec_b64 s[0:1], s[38:39]
	s_cbranch_execz .LBB0_1629
	v_lshl_add_u64 v[118:119], v[144:145], 2, s[42:43]
	s_waitcnt lgkmcnt(0)
	v_add_f32_e32 v1, v116, v117
	global_atomic_add_f32 v[118:119], v1, off
.LBB0_1629:
	s_or_b64 exec, exec, s[0:1]
	v_or_b32_e32 v116, 16, v144
	s_waitcnt lgkmcnt(0)
	v_ashrrev_i32_e32 v117, 31, v116
	v_lshlrev_b64 v[118:119], 13, v[116:117]
	v_lshl_add_u64 v[118:119], s[36:37], 0, v[118:119]
	v_lshl_add_u64 v[118:119], v[142:143], 1, v[118:119]
	s_waitcnt vmcnt(11)
	v_lshlrev_b32_e32 v130, 16, v164
	v_and_b32_e32 v131, 0xffff0000, v164
	v_lshlrev_b32_e32 v122, 16, v165
	v_and_b32_e32 v123, 0xffff0000, v165
	v_lshlrev_b32_e32 v150, 16, v166
	v_and_b32_e32 v151, 0xffff0000, v166
	v_lshlrev_b32_e32 v124, 16, v167
	v_and_b32_e32 v125, 0xffff0000, v167
	v_pk_add_f32 v[114:115], v[114:115], v[122:123]
	v_pk_add_f32 v[112:113], v[112:113], v[130:131]
	v_pk_add_f32 v[122:123], v[110:111], v[124:125]
	v_pk_add_f32 v[110:111], v[108:109], v[150:151]
	v_mul_f32_e32 v1, v113, v113
	v_mul_f32_e32 v108, v115, v115
	v_fmac_f32_e32 v1, v112, v112
	v_fmac_f32_e32 v108, v114, v114
	v_add_f32_e32 v1, v1, v108
	v_mul_f32_e32 v108, v111, v111
	v_fmac_f32_e32 v108, v110, v110
	v_add_f32_e32 v1, v108, v1
	v_mul_f32_e32 v108, v123, v123
	v_fmac_f32_e32 v108, v122, v122
	v_add_f32_e32 v1, v108, v1
	v_cvt_pk_bf16_f32 v108, v112, v113
	v_cvt_pk_bf16_f32 v109, v114, v115
	v_cvt_pk_bf16_f32 v110, v110, v111
	v_cvt_pk_bf16_f32 v111, v122, v123
	global_store_dwordx4 v[118:119], v[108:111], off
	v_lshlrev_b32_e32 v112, 16, v170
	v_and_b32_e32 v113, 0xffff0000, v170
	v_lshlrev_b32_e32 v108, 16, v168
	v_and_b32_e32 v109, 0xffff0000, v168
	v_lshlrev_b32_e32 v110, 16, v169
	v_and_b32_e32 v111, 0xffff0000, v169
	v_lshlrev_b32_e32 v114, 16, v171
	v_and_b32_e32 v115, 0xffff0000, v171
	v_pk_add_f32 v[106:107], v[106:107], v[110:111]
	v_pk_add_f32 v[104:105], v[104:105], v[108:109]
	v_pk_add_f32 v[108:109], v[102:103], v[114:115]
	v_pk_add_f32 v[102:103], v[100:101], v[112:113]
	v_mul_f32_e32 v100, v105, v105
	v_mul_f32_e32 v101, v107, v107
	v_fmac_f32_e32 v100, v104, v104
	v_fmac_f32_e32 v101, v106, v106
	v_add_f32_e32 v100, v100, v101
	v_mul_f32_e32 v101, v103, v103
	v_fmac_f32_e32 v101, v102, v102
	v_add_f32_e32 v100, v101, v100
	v_mul_f32_e32 v101, v109, v109
	v_fmac_f32_e32 v101, v108, v108
	v_add_f32_e32 v100, v101, v100
	v_add_f32_e32 v1, v1, v100
	v_cvt_pk_bf16_f32 v100, v104, v105
	v_cvt_pk_bf16_f32 v101, v106, v107
	v_cvt_pk_bf16_f32 v102, v102, v103
	v_cvt_pk_bf16_f32 v103, v108, v109
	global_store_dwordx4 v[118:119], v[100:103], off offset:256
	ds_bpermute_b32 v100, v120, v1
	s_waitcnt lgkmcnt(0)
	v_add_f32_e32 v100, v1, v100
	ds_bpermute_b32 v101, v121, v100
	s_and_saveexec_b64 s[0:1], s[38:39]
	s_cbranch_execz .LBB0_1631
	v_lshl_add_u64 v[102:103], v[116:117], 2, s[42:43]
	s_waitcnt lgkmcnt(0)
	v_add_f32_e32 v1, v100, v101
	global_atomic_add_f32 v[102:103], v1, off
; __device__ __forceinline__ unsigned pkbf(float lo, float hi) { f32x2v v = {lo, hi}; bf16x2v b = __builtin_convertvector(v, bf16x2v); return __builtin_bit_cast(unsigned, b); }
;     __device__ __forceinline__ void operator()(const f32x4 (&acc)[2][2][4][2], const Unit& u, int wr, int wc, int fr, int fq) const {
;     ...
;                 const int r = row0 + ai * HALF + m * 16;
;                 bf16_t* xp = XB + (size_t)r * 4096 + col0; float sq = 0.f;
;                 const u32x4 o0 = *(const u32x4*)xp, o1 = *(const u32x4*)(xp + HALF);
; #pragma unroll
;                 for (int bj = 0; bj < 2; ++bj) {
;                     const u32x4 o = bj ? o1 : o0;
;                     f32x4 a = {__uint_as_float(o.x << 16), __uint_as_float(o.x & 0xffff0000u), __uint_as_float(o.y << 16), __uint_as_float(o.y & 0xffff0000u)};
;                     f32x4 b = {__uint_as_float(o.z << 16), __uint_as_float(o.z & 0xffff0000u), __uint_as_float(o.w << 16), __uint_as_float(o.w & 0xffff0000u)};
;                     a += acc[ai][bj][m][0]; b += acc[ai][bj][m][1];
;                     if (Y) { float* yp = Y + (size_t)r * 4096 + col0 + bj * HALF; *(f32x4*)yp = a; *(f32x4*)(yp + 4) = b; }
;                     else {
;                         sq += (a[0] * a[0] + a[1] * a[1]) + (a[2] * a[2] + a[3] * a[3]) + (b[0] * b[0] + b[1] * b[1]) + (b[2] * b[2] + b[3] * b[3]);
;                         u32x4 w; w.x = pkbf(a[0], a[1]); w.y = pkbf(a[2], a[3]); w.z = pkbf(b[0], b[1]); w.w = pkbf(b[2], b[3]);
;                         *(u32x4*)(xp + bj * HALF) = w; } }
;                 if (!Y) { sq += __shfl_xor(sq, 16); sq += __shfl_xor(sq, 32); if (fq == 0) unsafeAtomicAdd(ssq + r, sq); }
;             }
.LBB0_1631:
	s_or_b64 exec, exec, s[0:1]
	s_mov_b64 s[100:101], 0x140000
	v_lshl_add_u64 v[204:205], v[158:159], 0, s[100:101]
	global_load_dwordx4 v[164:167], v[204:205], off
	global_load_dwordx4 v[168:171], v[204:205], off offset:256
	v_or_b32_e32 v100, 32, v144
	s_waitcnt lgkmcnt(0)
	v_ashrrev_i32_e32 v101, 31, v100
	v_lshlrev_b64 v[102:103], 13, v[100:101]
	v_lshl_add_u64 v[102:103], s[36:37], 0, v[102:103]
	v_lshl_add_u64 v[102:103], v[142:143], 1, v[102:103]
	s_waitcnt vmcnt(14)
	v_lshlrev_b32_e32 v112, 16, v172
	v_and_b32_e32 v113, 0xffff0000, v172
	v_lshlrev_b32_e32 v104, 16, v173
	v_and_b32_e32 v105, 0xffff0000, v173
	v_lshlrev_b32_e32 v114, 16, v174
	v_and_b32_e32 v115, 0xffff0000, v174
	v_lshlrev_b32_e32 v106, 16, v175
	v_and_b32_e32 v107, 0xffff0000, v175
	v_pk_add_f32 v[98:99], v[98:99], v[104:105]
	v_pk_add_f32 v[96:97], v[96:97], v[112:113]
	v_pk_add_f32 v[104:105], v[94:95], v[106:107]
	v_pk_add_f32 v[94:95], v[92:93], v[114:115]
	v_mul_f32_e32 v1, v97, v97
	v_mul_f32_e32 v92, v99, v99
	v_fmac_f32_e32 v1, v96, v96
	v_fmac_f32_e32 v92, v98, v98
	v_add_f32_e32 v1, v1, v92
	v_mul_f32_e32 v92, v95, v95
	v_fmac_f32_e32 v92, v94, v94
	v_add_f32_e32 v1, v92, v1
	v_mul_f32_e32 v92, v105, v105
	v_fmac_f32_e32 v92, v104, v104
	v_add_f32_e32 v1, v92, v1
	v_cvt_pk_bf16_f32 v92, v96, v97
	v_cvt_pk_bf16_f32 v93, v98, v99
	v_cvt_pk_bf16_f32 v94, v94, v95
	v_cvt_pk_bf16_f32 v95, v104, v105
	global_store_dwordx4 v[102:103], v[92:95], off
	v_lshlrev_b32_e32 v96, 16, v178
	v_and_b32_e32 v97, 0xffff0000, v178
	v_lshlrev_b32_e32 v92, 16, v176
	v_and_b32_e32 v93, 0xffff0000, v176
	v_lshlrev_b32_e32 v94, 16, v177
	v_and_b32_e32 v95, 0xffff0000, v177
	v_lshlrev_b32_e32 v98, 16, v179
	v_and_b32_e32 v99, 0xffff0000, v179
	v_pk_add_f32 v[90:91], v[90:91], v[94:95]
	v_pk_add_f32 v[88:89], v[88:89], v[92:93]
	v_pk_add_f32 v[92:93], v[86:87], v[98:99]
	v_pk_add_f32 v[86:87], v[84:85], v[96:97]
	v_mul_f32_e32 v84, v89, v89
	v_mul_f32_e32 v85, v91, v91
	v_fmac_f32_e32 v84, v88, v88
	v_fmac_f32_e32 v85, v90, v90
	v_add_f32_e32 v84, v84, v85
	v_mul_f32_e32 v85, v87, v87
	v_fmac_f32_e32 v85, v86, v86
	v_add_f32_e32 v84, v85, v84
	v_mul_f32_e32 v85, v93, v93
	v_fmac_f32_e32 v85, v92, v92
	v_add_f32_e32 v84, v85, v84
	v_add_f32_e32 v1, v1, v84
	v_cvt_pk_bf16_f32 v84, v88, v89
	v_cvt_pk_bf16_f32 v85, v90, v91
	v_cvt_pk_bf16_f32 v86, v86, v87
	v_cvt_pk_bf16_f32 v87, v92, v93
	global_store_dwordx4 v[102:103], v[84:87], off offset:256
	ds_bpermute_b32 v84, v120, v1
	s_waitcnt lgkmcnt(0)
	v_add_f32_e32 v84, v1, v84
	ds_bpermute_b32 v85, v121, v84
	s_and_saveexec_b64 s[0:1], s[38:39]
	s_cbranch_execz .LBB0_1633
	v_lshl_add_u64 v[86:87], v[100:101], 2, s[42:43]
	s_waitcnt lgkmcnt(0)
	v_add_f32_e32 v1, v84, v85
	global_atomic_add_f32 v[86:87], v1, off
.LBB0_1633:
	s_or_b64 exec, exec, s[0:1]
	s_mov_b64 s[100:101], 0x160000
	v_lshl_add_u64 v[204:205], v[158:159], 0, s[100:101]
	global_load_dwordx4 v[172:175], v[204:205], off
	global_load_dwordx4 v[176:179], v[204:205], off offset:256
	v_or_b32_e32 v84, 48, v144
	s_waitcnt lgkmcnt(0)
	v_ashrrev_i32_e32 v85, 31, v84
	v_lshlrev_b64 v[86:87], 13, v[84:85]
	v_lshl_add_u64 v[86:87], s[36:37], 0, v[86:87]
	v_lshl_add_u64 v[86:87], v[142:143], 1, v[86:87]
	s_waitcnt vmcnt(17)
	v_lshlrev_b32_e32 v96, 16, v180
	v_and_b32_e32 v97, 0xffff0000, v180
	v_lshlrev_b32_e32 v88, 16, v181
	v_and_b32_e32 v89, 0xffff0000, v181
	v_lshlrev_b32_e32 v98, 16, v182
	v_and_b32_e32 v99, 0xffff0000, v182
	v_lshlrev_b32_e32 v90, 16, v183
	v_and_b32_e32 v91, 0xffff0000, v183
	v_pk_add_f32 v[82:83], v[82:83], v[88:89]
	v_pk_add_f32 v[80:81], v[80:81], v[96:97]
	v_pk_add_f32 v[88:89], v[78:79], v[90:91]
	v_pk_add_f32 v[78:79], v[76:77], v[98:99]
	v_mul_f32_e32 v1, v81, v81
	v_mul_f32_e32 v76, v83, v83
	v_fmac_f32_e32 v1, v80, v80
	v_fmac_f32_e32 v76, v82, v82
	v_add_f32_e32 v1, v1, v76
	v_mul_f32_e32 v76, v79, v79
	v_fmac_f32_e32 v76, v78, v78
	v_add_f32_e32 v1, v76, v1
	v_mul_f32_e32 v76, v89, v89
	v_fmac_f32_e32 v76, v88, v88
	v_add_f32_e32 v1, v76, v1
	v_cvt_pk_bf16_f32 v76, v80, v81
	v_cvt_pk_bf16_f32 v77, v82, v83
	v_cvt_pk_bf16_f32 v78, v78, v79
	v_cvt_pk_bf16_f32 v79, v88, v89
	global_store_dwordx4 v[86:87], v[76:79], off
	v_lshlrev_b32_e32 v80, 16, v186
	v_and_b32_e32 v81, 0xffff0000, v186
	v_lshlrev_b32_e32 v76, 16, v184
	v_and_b32_e32 v77, 0xffff0000, v184
	v_lshlrev_b32_e32 v78, 16, v185
	v_and_b32_e32 v79, 0xffff0000, v185
	v_lshlrev_b32_e32 v82, 16, v187
	v_and_b32_e32 v83, 0xffff0000, v187
	v_pk_add_f32 v[74:75], v[74:75], v[78:79]
	v_pk_add_f32 v[72:73], v[72:73], v[76:77]
	v_pk_add_f32 v[76:77], v[70:71], v[82:83]
	v_pk_add_f32 v[70:71], v[68:69], v[80:81]
	v_mul_f32_e32 v68, v73, v73
	v_mul_f32_e32 v69, v75, v75
	v_fmac_f32_e32 v68, v72, v72
	v_fmac_f32_e32 v69, v74, v74
	v_add_f32_e32 v68, v68, v69
	v_mul_f32_e32 v69, v71, v71
	v_fmac_f32_e32 v69, v70, v70
	v_add_f32_e32 v68, v69, v68
	v_mul_f32_e32 v69, v77, v77
	v_fmac_f32_e32 v69, v76, v76
	v_add_f32_e32 v68, v69, v68
	v_add_f32_e32 v1, v1, v68
	v_cvt_pk_bf16_f32 v68, v72, v73
	v_cvt_pk_bf16_f32 v69, v74, v75
	v_cvt_pk_bf16_f32 v70, v70, v71
	v_cvt_pk_bf16_f32 v71, v76, v77
	global_store_dwordx4 v[86:87], v[68:71], off offset:256
	ds_bpermute_b32 v68, v120, v1
	s_waitcnt lgkmcnt(0)
	v_add_f32_e32 v68, v1, v68
	ds_bpermute_b32 v69, v121, v68
	s_and_saveexec_b64 s[0:1], s[38:39]
	s_cbranch_execz .LBB0_1635
	v_lshl_add_u64 v[70:71], v[84:85], 2, s[42:43]
	s_waitcnt lgkmcnt(0)
	v_add_f32_e32 v1, v68, v69
	global_atomic_add_f32 v[70:71], v1, off
; __device__ __forceinline__ unsigned pkbf(float lo, float hi) { f32x2v v = {lo, hi}; bf16x2v b = __builtin_convertvector(v, bf16x2v); return __builtin_bit_cast(unsigned, b); }
;     __device__ __forceinline__ void operator()(const f32x4 (&acc)[2][2][4][2], const Unit& u, int wr, int wc, int fr, int fq) const {
;     ...
;                 const int r = row0 + ai * HALF + m * 16;
;                 bf16_t* xp = XB + (size_t)r * 4096 + col0; float sq = 0.f;
;                 const u32x4 o0 = *(const u32x4*)xp, o1 = *(const u32x4*)(xp + HALF);
; #pragma unroll
;                 for (int bj = 0; bj < 2; ++bj) {
;                     const u32x4 o = bj ? o1 : o0;
;                     f32x4 a = {__uint_as_float(o.x << 16), __uint_as_float(o.x & 0xffff0000u), __uint_as_float(o.y << 16), __uint_as_float(o.y & 0xffff0000u)};
;                     f32x4 b = {__uint_as_float(o.z << 16), __uint_as_float(o.z & 0xffff0000u), __uint_as_float(o.w << 16), __uint_as_float(o.w & 0xffff0000u)};
;                     a += acc[ai][bj][m][0]; b += acc[ai][bj][m][1];
;                     if (Y) { float* yp = Y + (size_t)r * 4096 + col0 + bj * HALF; *(f32x4*)yp = a; *(f32x4*)(yp + 4) = b; }
;                     else {
;                         sq += (a[0] * a[0] + a[1] * a[1]) + (a[2] * a[2] + a[3] * a[3]) + (b[0] * b[0] + b[1] * b[1]) + (b[2] * b[2] + b[3] * b[3]);
;                         u32x4 w; w.x = pkbf(a[0], a[1]); w.y = pkbf(a[2], a[3]); w.z = pkbf(b[0], b[1]); w.w = pkbf(b[2], b[3]);
;                         *(u32x4*)(xp + bj * HALF) = w; } }
;                 if (!Y) { sq += __shfl_xor(sq, 16); sq += __shfl_xor(sq, 32); if (fq == 0) unsafeAtomicAdd(ssq + r, sq); }
;             }
.LBB0_1635:
	s_or_b64 exec, exec, s[0:1]
	v_add_u32_e32 v68, 0x80, v144
	s_waitcnt lgkmcnt(0)
	v_ashrrev_i32_e32 v69, 31, v68
	v_lshlrev_b64 v[70:71], 13, v[68:69]
	v_lshl_add_u64 v[70:71], s[36:37], 0, v[70:71]
	v_lshl_add_u64 v[70:71], v[142:143], 1, v[70:71]
	s_waitcnt vmcnt(18)
	v_lshlrev_b32_e32 v80, 16, v188
	v_and_b32_e32 v81, 0xffff0000, v188
	v_lshlrev_b32_e32 v72, 16, v189
	v_and_b32_e32 v73, 0xffff0000, v189
	v_lshlrev_b32_e32 v82, 16, v190
	v_and_b32_e32 v83, 0xffff0000, v190
	v_lshlrev_b32_e32 v74, 16, v191
	v_and_b32_e32 v75, 0xffff0000, v191
	v_pk_add_f32 v[66:67], v[66:67], v[72:73]
	v_pk_add_f32 v[64:65], v[64:65], v[80:81]
	v_pk_add_f32 v[72:73], v[62:63], v[74:75]
	v_pk_add_f32 v[62:63], v[60:61], v[82:83]
	v_mul_f32_e32 v1, v65, v65
	v_mul_f32_e32 v60, v67, v67
	v_fmac_f32_e32 v1, v64, v64
	v_fmac_f32_e32 v60, v66, v66
	v_add_f32_e32 v1, v1, v60
	v_mul_f32_e32 v60, v63, v63
	v_fmac_f32_e32 v60, v62, v62
	v_add_f32_e32 v1, v60, v1
	v_mul_f32_e32 v60, v73, v73
	v_fmac_f32_e32 v60, v72, v72
	v_add_f32_e32 v1, v60, v1
	v_cvt_pk_bf16_f32 v60, v64, v65
	v_cvt_pk_bf16_f32 v61, v66, v67
	v_cvt_pk_bf16_f32 v62, v62, v63
	v_cvt_pk_bf16_f32 v63, v72, v73
	global_store_dwordx4 v[70:71], v[60:63], off
	v_lshlrev_b32_e32 v64, 16, v194
	v_and_b32_e32 v65, 0xffff0000, v194
	v_lshlrev_b32_e32 v60, 16, v192
	v_and_b32_e32 v61, 0xffff0000, v192
	v_lshlrev_b32_e32 v62, 16, v193
	v_and_b32_e32 v63, 0xffff0000, v193
	v_lshlrev_b32_e32 v66, 16, v195
	v_and_b32_e32 v67, 0xffff0000, v195
	v_pk_add_f32 v[58:59], v[58:59], v[62:63]
	v_pk_add_f32 v[56:57], v[56:57], v[60:61]
	v_pk_add_f32 v[60:61], v[54:55], v[66:67]
	v_pk_add_f32 v[54:55], v[52:53], v[64:65]
	v_mul_f32_e32 v52, v57, v57
	v_mul_f32_e32 v53, v59, v59
	v_fmac_f32_e32 v52, v56, v56
	v_fmac_f32_e32 v53, v58, v58
	v_add_f32_e32 v52, v52, v53
	v_mul_f32_e32 v53, v55, v55
	v_fmac_f32_e32 v53, v54, v54
	v_add_f32_e32 v52, v53, v52
	v_mul_f32_e32 v53, v61, v61
	v_fmac_f32_e32 v53, v60, v60
	v_add_f32_e32 v52, v53, v52
	v_add_f32_e32 v1, v1, v52
	v_cvt_pk_bf16_f32 v52, v56, v57
	v_cvt_pk_bf16_f32 v53, v58, v59
	v_cvt_pk_bf16_f32 v54, v54, v55
	v_cvt_pk_bf16_f32 v55, v60, v61
	global_store_dwordx4 v[70:71], v[52:55], off offset:256
	ds_bpermute_b32 v52, v120, v1
	s_waitcnt lgkmcnt(0)
	v_add_f32_e32 v52, v1, v52
	ds_bpermute_b32 v53, v121, v52
	s_and_saveexec_b64 s[0:1], s[38:39]
	s_cbranch_execz .LBB0_1637
	v_lshl_add_u64 v[54:55], v[68:69], 2, s[42:43]
	s_waitcnt lgkmcnt(0)
	v_add_f32_e32 v1, v52, v53
	global_atomic_add_f32 v[54:55], v1, off
.LBB0_1637:
	s_or_b64 exec, exec, s[0:1]
	v_add_u32_e32 v52, 0x90, v144
	s_waitcnt lgkmcnt(0)
	v_ashrrev_i32_e32 v53, 31, v52
	v_lshlrev_b64 v[54:55], 13, v[52:53]
	v_lshl_add_u64 v[54:55], s[36:37], 0, v[54:55]
	v_lshl_add_u64 v[54:55], v[142:143], 1, v[54:55]
	s_waitcnt vmcnt(19)
	v_lshlrev_b32_e32 v64, 16, v196
	v_and_b32_e32 v65, 0xffff0000, v196
	v_lshlrev_b32_e32 v56, 16, v197
	v_and_b32_e32 v57, 0xffff0000, v197
	v_lshlrev_b32_e32 v66, 16, v198
	v_and_b32_e32 v67, 0xffff0000, v198
	v_lshlrev_b32_e32 v58, 16, v199
	v_and_b32_e32 v59, 0xffff0000, v199
	v_pk_add_f32 v[50:51], v[50:51], v[56:57]
	v_pk_add_f32 v[48:49], v[48:49], v[64:65]
	v_pk_add_f32 v[56:57], v[46:47], v[58:59]
	v_pk_add_f32 v[46:47], v[44:45], v[66:67]
	v_mul_f32_e32 v1, v49, v49
	v_mul_f32_e32 v44, v51, v51
	v_fmac_f32_e32 v1, v48, v48
	v_fmac_f32_e32 v44, v50, v50
	v_add_f32_e32 v1, v1, v44
	v_mul_f32_e32 v44, v47, v47
	v_fmac_f32_e32 v44, v46, v46
	v_add_f32_e32 v1, v44, v1
	v_mul_f32_e32 v44, v57, v57
	v_fmac_f32_e32 v44, v56, v56
	v_add_f32_e32 v1, v44, v1
	v_cvt_pk_bf16_f32 v44, v48, v49
	v_cvt_pk_bf16_f32 v45, v50, v51
	v_cvt_pk_bf16_f32 v46, v46, v47
	v_cvt_pk_bf16_f32 v47, v56, v57
	global_store_dwordx4 v[54:55], v[44:47], off
	v_lshlrev_b32_e32 v48, 16, v202
	v_and_b32_e32 v49, 0xffff0000, v202
	v_lshlrev_b32_e32 v44, 16, v200
	v_and_b32_e32 v45, 0xffff0000, v200
	v_lshlrev_b32_e32 v46, 16, v201
	v_and_b32_e32 v47, 0xffff0000, v201
	v_lshlrev_b32_e32 v50, 16, v203
	v_and_b32_e32 v51, 0xffff0000, v203
	v_pk_add_f32 v[42:43], v[42:43], v[46:47]
	v_pk_add_f32 v[40:41], v[40:41], v[44:45]
	v_pk_add_f32 v[44:45], v[38:39], v[50:51]
	v_pk_add_f32 v[38:39], v[36:37], v[48:49]
	v_mul_f32_e32 v36, v41, v41
	v_mul_f32_e32 v37, v43, v43
	v_fmac_f32_e32 v36, v40, v40
	v_fmac_f32_e32 v37, v42, v42
	v_add_f32_e32 v36, v36, v37
	v_mul_f32_e32 v37, v39, v39
	v_fmac_f32_e32 v37, v38, v38
	v_add_f32_e32 v36, v37, v36
	v_mul_f32_e32 v37, v45, v45
	v_fmac_f32_e32 v37, v44, v44
	v_add_f32_e32 v36, v37, v36
	v_add_f32_e32 v1, v1, v36
	v_cvt_pk_bf16_f32 v36, v40, v41
	v_cvt_pk_bf16_f32 v37, v42, v43
	v_cvt_pk_bf16_f32 v38, v38, v39
	v_cvt_pk_bf16_f32 v39, v44, v45
	global_store_dwordx4 v[54:55], v[36:39], off offset:256
	ds_bpermute_b32 v36, v120, v1
	s_waitcnt lgkmcnt(0)
	v_add_f32_e32 v36, v1, v36
	ds_bpermute_b32 v37, v121, v36
	s_and_saveexec_b64 s[0:1], s[38:39]
	s_cbranch_execz .LBB0_1639
	v_lshl_add_u64 v[38:39], v[52:53], 2, s[42:43]
	s_waitcnt lgkmcnt(0)
	v_add_f32_e32 v1, v36, v37
	global_atomic_add_f32 v[38:39], v1, off
; __device__ __forceinline__ unsigned pkbf(float lo, float hi) { f32x2v v = {lo, hi}; bf16x2v b = __builtin_convertvector(v, bf16x2v); return __builtin_bit_cast(unsigned, b); }
;     __device__ __forceinline__ void operator()(const f32x4 (&acc)[2][2][4][2], const Unit& u, int wr, int wc, int fr, int fq) const {
;     ...
;                 const int r = row0 + ai * HALF + m * 16;
;                 bf16_t* xp = XB + (size_t)r * 4096 + col0; float sq = 0.f;
;                 const u32x4 o0 = *(const u32x4*)xp, o1 = *(const u32x4*)(xp + HALF);
; #pragma unroll
;                 for (int bj = 0; bj < 2; ++bj) {
;                     const u32x4 o = bj ? o1 : o0;
;                     f32x4 a = {__uint_as_float(o.x << 16), __uint_as_float(o.x & 0xffff0000u), __uint_as_float(o.y << 16), __uint_as_float(o.y & 0xffff0000u)};
;                     f32x4 b = {__uint_as_float(o.z << 16), __uint_as_float(o.z & 0xffff0000u), __uint_as_float(o.w << 16), __uint_as_float(o.w & 0xffff0000u)};
;                     a += acc[ai][bj][m][0]; b += acc[ai][bj][m][1];
;                     if (Y) { float* yp = Y + (size_t)r * 4096 + col0 + bj * HALF; *(f32x4*)yp = a; *(f32x4*)(yp + 4) = b; }
;                     else {
;                         sq += (a[0] * a[0] + a[1] * a[1]) + (a[2] * a[2] + a[3] * a[3]) + (b[0] * b[0] + b[1] * b[1]) + (b[2] * b[2] + b[3] * b[3]);
;                         u32x4 w; w.x = pkbf(a[0], a[1]); w.y = pkbf(a[2], a[3]); w.z = pkbf(b[0], b[1]); w.w = pkbf(b[2], b[3]);
;                         *(u32x4*)(xp + bj * HALF) = w; } }
;                 if (!Y) { sq += __shfl_xor(sq, 16); sq += __shfl_xor(sq, 32); if (fq == 0) unsafeAtomicAdd(ssq + r, sq); }
;             }
.LBB0_1639:
	s_or_b64 exec, exec, s[0:1]
	v_add_u32_e32 v36, 0xa0, v144
	s_waitcnt lgkmcnt(0)
	v_ashrrev_i32_e32 v37, 31, v36
	v_lshlrev_b64 v[38:39], 13, v[36:37]
	v_lshl_add_u64 v[38:39], s[36:37], 0, v[38:39]
	v_lshl_add_u64 v[38:39], v[142:143], 1, v[38:39]
	s_waitcnt vmcnt(14)
	v_lshlrev_b32_e32 v48, 16, v164
	v_and_b32_e32 v49, 0xffff0000, v164
	v_lshlrev_b32_e32 v40, 16, v165
	v_and_b32_e32 v41, 0xffff0000, v165
	v_lshlrev_b32_e32 v50, 16, v166
	v_and_b32_e32 v51, 0xffff0000, v166
	v_lshlrev_b32_e32 v42, 16, v167
	v_and_b32_e32 v43, 0xffff0000, v167
	v_pk_add_f32 v[34:35], v[34:35], v[40:41]
	v_pk_add_f32 v[32:33], v[32:33], v[48:49]
	v_pk_add_f32 v[40:41], v[30:31], v[42:43]
	v_pk_add_f32 v[30:31], v[28:29], v[50:51]
	v_mul_f32_e32 v1, v33, v33
	v_mul_f32_e32 v28, v35, v35
	v_fmac_f32_e32 v1, v32, v32
	v_fmac_f32_e32 v28, v34, v34
	v_add_f32_e32 v1, v1, v28
	v_mul_f32_e32 v28, v31, v31
	v_fmac_f32_e32 v28, v30, v30
	v_add_f32_e32 v1, v28, v1
	v_mul_f32_e32 v28, v41, v41
	v_fmac_f32_e32 v28, v40, v40
	v_add_f32_e32 v1, v28, v1
	v_cvt_pk_bf16_f32 v28, v32, v33
	v_cvt_pk_bf16_f32 v29, v34, v35
	v_cvt_pk_bf16_f32 v30, v30, v31
	v_cvt_pk_bf16_f32 v31, v40, v41
	global_store_dwordx4 v[38:39], v[28:31], off
	v_lshlrev_b32_e32 v32, 16, v170
	v_and_b32_e32 v33, 0xffff0000, v170
	v_lshlrev_b32_e32 v28, 16, v168
	v_and_b32_e32 v29, 0xffff0000, v168
	v_lshlrev_b32_e32 v30, 16, v169
	v_and_b32_e32 v31, 0xffff0000, v169
	v_lshlrev_b32_e32 v34, 16, v171
	v_and_b32_e32 v35, 0xffff0000, v171
	v_pk_add_f32 v[26:27], v[26:27], v[30:31]
	v_pk_add_f32 v[24:25], v[24:25], v[28:29]
	v_pk_add_f32 v[28:29], v[22:23], v[34:35]
	v_pk_add_f32 v[22:23], v[20:21], v[32:33]
	v_mul_f32_e32 v20, v25, v25
	v_mul_f32_e32 v21, v27, v27
	v_fmac_f32_e32 v20, v24, v24
	v_fmac_f32_e32 v21, v26, v26
	v_add_f32_e32 v20, v20, v21
	v_mul_f32_e32 v21, v23, v23
	v_fmac_f32_e32 v21, v22, v22
	v_add_f32_e32 v20, v21, v20
	v_mul_f32_e32 v21, v29, v29
	v_fmac_f32_e32 v21, v28, v28
	v_add_f32_e32 v20, v21, v20
	v_add_f32_e32 v1, v1, v20
	v_cvt_pk_bf16_f32 v20, v24, v25
	v_cvt_pk_bf16_f32 v21, v26, v27
	v_cvt_pk_bf16_f32 v22, v22, v23
	v_cvt_pk_bf16_f32 v23, v28, v29
	global_store_dwordx4 v[38:39], v[20:23], off offset:256
	ds_bpermute_b32 v20, v120, v1
	s_waitcnt lgkmcnt(0)
	v_add_f32_e32 v20, v1, v20
	ds_bpermute_b32 v21, v121, v20
	s_and_saveexec_b64 s[0:1], s[38:39]
	s_cbranch_execz .LBB0_1641
	v_lshl_add_u64 v[22:23], v[36:37], 2, s[42:43]
	s_waitcnt lgkmcnt(0)
	v_add_f32_e32 v1, v20, v21
	global_atomic_add_f32 v[22:23], v1, off
.LBB0_1641:
	s_or_b64 exec, exec, s[0:1]
	v_add_u32_e32 v20, 0xb0, v144
	s_waitcnt lgkmcnt(0)
	v_ashrrev_i32_e32 v21, 31, v20
	v_lshlrev_b64 v[22:23], 13, v[20:21]
	v_lshl_add_u64 v[22:23], s[36:37], 0, v[22:23]
	v_lshl_add_u64 v[22:23], v[142:143], 1, v[22:23]
	s_waitcnt vmcnt(12)
	v_lshlrev_b32_e32 v32, 16, v172
	v_and_b32_e32 v33, 0xffff0000, v172
	v_lshlrev_b32_e32 v24, 16, v173
	v_and_b32_e32 v25, 0xffff0000, v173
	v_lshlrev_b32_e32 v34, 16, v174
	v_and_b32_e32 v35, 0xffff0000, v174
	v_lshlrev_b32_e32 v26, 16, v175
	v_and_b32_e32 v27, 0xffff0000, v175
	v_pk_add_f32 v[18:19], v[18:19], v[24:25]
	v_pk_add_f32 v[16:17], v[16:17], v[32:33]
	v_pk_add_f32 v[24:25], v[14:15], v[26:27]
	v_pk_add_f32 v[14:15], v[12:13], v[34:35]
	v_mul_f32_e32 v1, v17, v17
	v_mul_f32_e32 v12, v19, v19
	v_fmac_f32_e32 v1, v16, v16
	v_fmac_f32_e32 v12, v18, v18
	v_add_f32_e32 v1, v1, v12
	v_mul_f32_e32 v12, v15, v15
	v_fmac_f32_e32 v12, v14, v14
	v_add_f32_e32 v1, v12, v1
	v_mul_f32_e32 v12, v25, v25
	v_fmac_f32_e32 v12, v24, v24
	v_add_f32_e32 v1, v12, v1
	v_cvt_pk_bf16_f32 v12, v16, v17
	v_cvt_pk_bf16_f32 v13, v18, v19
	v_cvt_pk_bf16_f32 v14, v14, v15
	v_cvt_pk_bf16_f32 v15, v24, v25
	global_store_dwordx4 v[22:23], v[12:15], off
	v_lshlrev_b32_e32 v16, 16, v178
	v_and_b32_e32 v17, 0xffff0000, v178
	v_lshlrev_b32_e32 v12, 16, v176
	v_and_b32_e32 v13, 0xffff0000, v176
	v_lshlrev_b32_e32 v14, 16, v177
	v_and_b32_e32 v15, 0xffff0000, v177
	v_lshlrev_b32_e32 v18, 16, v179
	v_and_b32_e32 v19, 0xffff0000, v179
	v_pk_add_f32 v[10:11], v[10:11], v[14:15]
	v_pk_add_f32 v[8:9], v[8:9], v[12:13]
	v_pk_add_f32 v[12:13], v[6:7], v[18:19]
	v_pk_add_f32 v[6:7], v[4:5], v[16:17]
	v_mul_f32_e32 v4, v9, v9
	v_mul_f32_e32 v5, v11, v11
	v_fmac_f32_e32 v4, v8, v8
	v_fmac_f32_e32 v5, v10, v10
	v_add_f32_e32 v4, v4, v5
	v_mul_f32_e32 v5, v7, v7
	v_fmac_f32_e32 v5, v6, v6
	v_add_f32_e32 v4, v5, v4
	v_mul_f32_e32 v5, v13, v13
	v_fmac_f32_e32 v5, v12, v12
	v_add_f32_e32 v4, v5, v4
	v_add_f32_e32 v1, v1, v4
	v_cvt_pk_bf16_f32 v4, v8, v9
	v_cvt_pk_bf16_f32 v5, v10, v11
	v_cvt_pk_bf16_f32 v6, v6, v7
	v_cvt_pk_bf16_f32 v7, v12, v13
	global_store_dwordx4 v[22:23], v[4:7], off offset:256
	ds_bpermute_b32 v4, v120, v1
	s_waitcnt lgkmcnt(0)
	v_add_f32_e32 v4, v1, v4
	ds_bpermute_b32 v5, v121, v4
	s_and_saveexec_b64 s[0:1], s[38:39]
	s_cbranch_execz .LBB0_1643
	s_waitcnt lgkmcnt(0)
	v_add_f32_e32 v1, v4, v5
	v_lshl_add_u64 v[4:5], v[20:21], 2, s[42:43]
	global_atomic_add_f32 v[4:5], v1, off
